# P4: next GLA unit's start loads prefetched one unit ahead into spare registers
# baseline (speedup 1.0000x reference)
; #define LAS __attribute__((address_space(3)))
; #define GLA_HEAD_CONSTS(hh) float wu_[16]; { const int col_ = (hh) * 128 + (tid & 127); _Pragma("unroll") for (int j = 0; j < 16; ++j) wu_[j] = a.in[I_WUP][j * 512 + col_]; } const float bd_ = a.in[I_BDEC][(hh) * 128 + (tid & 127)]
; #define PH(k) if (a.ph_lo <= (k) && (k) < a.ph_hi) { if ((k) > a.ph_lo && (k) != 6) SEAM(k);
; template <int MODE, bool dry = false>
; __device__ __forceinline__ void gla_unit(const Args& a, LAS unsigned char* lds, int idx, int h, int tid, const float (&wu)[16], float bd) {
;     ...
;     bf16x8 vraw[C / 16];
;     { const int t = tid & (C - 1), g0 = tid / C;
; #pragma unroll
;         for (int gi = 0; gi < C / 16; ++gi) vraw[gi] = *(const bf16x8*)(VB + (size_t)(row0 + t) * 1024 + h * 256 + 8 * (g0 * (C / 16) + gi)); }
;     bf16x8 sraw[4][2];
;     if (MODE == 1) {
; #pragma unroll
;         for (int ks = 0; ks < 4; ++ks)
; #pragma unroll
;             for (int m = 0; m < 2; ++m) sraw[ks][m] = *(const bf16x8*)(US + (size_t)(32 * wave + 16 * m + fr) * 128 + 32 * ks + 8 * kq); }
;     LAS f32x4* dlrL = (LAS f32x4*)(lds + G_DLR);
;     if (tid < C * 4) dlrL[tid] = ((const f32x4*)(DLR + (size_t)row0 * 16))[tid];
; __global__ void __launch_bounds__(512) fwd_kernel(Args a) {
;     ...
;     PH(4) { GLA_HEAD_CONSTS(bx & 3);
;         for (int u = bx; u < 1024; u += G) {
;             if ((G & 3) != 0) { const int col_ = (u & 3) * 128 + (tid & 127); for (int j = 0; j < 16; ++j) wu_[j] = a.in[I_WUP][j * 512 + col_]; }
;             const float bdu = (G & 3) ? a.in[I_BDEC][(u & 3) * 128 + (tid & 127)] : bd_;
;             gla_unit<1>(a, lds, u >> 2, u & 3, tid, wu_, bdu); }
.LBB0_725:
	s_cmpk_gt_i32 s2, 0x3ff
	s_cbranch_scc1 .LBB0_745
	s_lshl_b32 s0, s2, 7
	s_and_b32 s0, s0, 0x180
	s_waitcnt vmcnt(0)
	v_and_b32_e32 v71, 0x7f, v178
	v_or_b32_e32 v0, s0, v71
	v_lshlrev_b32_e32 v64, 2, v0
	v_mov_b32_e32 v65, 0
	s_add_i32 s0, 0, 0x18400
	v_lshlrev_b32_e32 v3, 2, v71
	v_add_u32_e32 v78, s0, v3
	v_lshl_add_u64 v[14:15], s[16:17], 0, v[64:65]
	s_movk_i32 s0, 0x1000
	v_add_co_u32_e32 v16, vcc, s0, v14
	s_movk_i32 s0, 0x2000
	s_nop 0
	v_addc_co_u32_e32 v17, vcc, 0, v15, vcc
	v_add_co_u32_e32 v10, vcc, s0, v14
	s_movk_i32 s0, 0x3000
	s_nop 0
	v_addc_co_u32_e32 v11, vcc, 0, v15, vcc
	v_add_co_u32_e32 v18, vcc, s0, v14
	s_movk_i32 s0, 0x4000
	s_nop 0
	v_addc_co_u32_e32 v19, vcc, 0, v15, vcc
	v_add_co_u32_e32 v20, vcc, s0, v14
	s_movk_i32 s0, 0x5000
	s_nop 0
	v_addc_co_u32_e32 v21, vcc, 0, v15, vcc
	v_add_co_u32_e32 v22, vcc, s0, v14
	s_movk_i32 s0, 0x6000
	s_nop 0
	v_addc_co_u32_e32 v23, vcc, 0, v15, vcc
	v_add_co_u32_e32 v24, vcc, s0, v14
	s_movk_i32 s0, 0x7000
	s_nop 0
	v_addc_co_u32_e32 v25, vcc, 0, v15, vcc
	global_load_dword v79, v64, s[18:19]
	global_load_dword v0, v64, s[16:17]
	global_load_dword v1, v64, s[16:17] offset:2048
	global_load_dword v2, v[10:11], off offset:-4096
	global_load_dword v4, v[10:11], off
	global_load_dword v5, v[10:11], off offset:2048
	global_load_dword v6, v[20:21], off offset:-4096
	global_load_dword v8, v[20:21], off
	global_load_dword v9, v[20:21], off offset:2048
	s_nop 0
	global_load_dword v10, v[24:25], off offset:-4096
	global_load_dword v12, v[24:25], off
	global_load_dword v13, v[24:25], off offset:2048
	v_add_co_u32_e32 v20, vcc, s0, v14
	s_and_b32 s0, s58, 3
	s_cmp_lg_u32 s0, 0
	s_cselect_b64 s[24:25], -1, 0
	s_add_u32 s26, s54, 0x5600000
	s_addc_u32 s27, s55, 0
	s_add_u32 s28, s54, 0x7800000
	s_addc_u32 s29, s55, 0
	s_add_u32 s30, s54, 0x6700000
	s_addc_u32 s31, s55, 0
	v_lshlrev_b32_e32 v24, 4, v178
	s_add_i32 s3, 0, 0x19800
	v_and_b32_e32 v80, 15, v178
	v_lshrrev_b32_e32 v7, 1, v178
	v_add_u32_e32 v81, s3, v24
	s_add_i32 s3, 0, 0x18e00
	v_and_b32_e32 v14, 0x1e0, v7
	v_lshrrev_b32_e32 v11, 4, v176
	v_and_b32_e32 v64, 48, v176
	v_add_u32_e32 v82, s3, v3
	v_or_b32_e32 v7, 31, v7
	s_add_i32 s3, 0, 0x16000
	v_mul_u32_u24_e32 v88, 0x110, v80
	v_addc_co_u32_e32 v21, vcc, 0, v15, vcc
	v_lshl_add_u32 v3, v176, 1, 0
	v_mul_u32_u24_e32 v15, 0x90, v14
	v_mul_u32_u24_e32 v7, 0x90, v7
	v_lshlrev_b32_e32 v84, 2, v11
	v_lshl_add_u32 v95, v11, 3, s3
	v_add3_u32 v11, v88, v64, 0
	v_lshl_add_u64 v[66:67], s[52:53], 0, v[64:65]
	v_add_u32_e32 v83, 0, v64
	v_add_u32_e32 v96, 0x4400, v11
	v_lshlrev_b32_e32 v64, 1, v14
	v_add_u32_e32 v97, v3, v15
	v_add_u32_e32 v98, v3, v7
	global_load_dword v3, v[16:17], off offset:2048
	global_load_dword v7, v[18:19], off offset:2048
	global_load_dword v11, v[22:23], off offset:2048
	global_load_dword v14, v[20:21], off
	global_load_dword v15, v[20:21], off offset:2048
	v_mov_b32_e32 v25, v65
	v_lshl_add_u64 v[26:27], s[52:53], 0, v[24:25]
	s_mov_b64 s[4:5], 0x4000000
	v_lshl_add_u64 v[68:69], v[26:27], 0, s[4:5]
	v_mbcnt_lo_u32_b32 v26, -1, 0
	v_mbcnt_hi_u32_b32 v26, -1, v26
	v_and_b32_e32 v28, 64, v26
	v_xor_b32_e32 v27, 16, v26
	v_add_u32_e32 v28, 64, v28
	v_cmp_lt_i32_e32 vcc, v27, v28
	v_and_b32_e32 v24, 48, v178
	s_add_i32 s6, 0, 0x19000
	v_cndmask_b32_e32 v27, v26, v27, vcc
	v_lshlrev_b32_e32 v89, 2, v27
	v_xor_b32_e32 v27, 32, v26
	v_cmp_lt_i32_e32 vcc, v27, v28
	s_movk_i32 s0, 0x100
	v_add_u32_e32 v70, 0, v24
	v_add_u32_e32 v24, s3, v24
	v_mul_u32_u24_e32 v25, 0x90, v80
	v_or_b32_e32 v85, 16, v80
	v_or_b32_e32 v86, 32, v80
	v_or_b32_e32 v87, 48, v80
	v_cndmask_b32_e32 v26, v26, v27, vcc
	s_add_u32 s34, s54, 0x9a00000
	s_mov_b32 s21, 0
	v_cmp_gt_u32_e64 s[0:1], s0, v178
	s_movk_i32 s41, 0x90
	s_movk_i32 s43, 0x110
	v_lshlrev_b32_e32 v90, 2, v26
	v_cmp_gt_u32_e64 s[4:5], 16, v176
	v_lshl_add_u32 v91, v80, 2, s6
	s_addc_u32 s35, s55, 0
	v_lshl_add_u32 v92, v85, 2, s6
	v_lshl_add_u32 v93, v86, 2, s6
	v_lshl_add_u32 v94, v87, 2, s6
	s_mov_b32 s60, 0xbfb8aa3b
	s_mov_b32 s61, 0x800000
	s_mov_b32 s62, 0x3f317217
	s_mov_b32 s63, 0x7f800000
	s_mov_b32 s64, 0x3d800000
	v_add_u32_e32 v99, v24, v25
	s_mov_b32 s40, 0x3b800000
	s_mov_b32 s42, 0x358637bd
	v_mov_b32_e32 v100, 0x41b17218
	s_mov_b32 s44, s2
	s_mov_b32 s98, s2
	s_lshl_b32 s99, s98, 4
	s_and_b32 s99, s99, 0xffffffc0
	v_or_b32_e32 v106, s99, v176
	v_mov_b32_e32 v107, v65
	v_lshlrev_b64 v[106:107], 11, v[106:107]
	v_lshl_add_u64 v[106:107], s[28:29], 0, v[106:107]
	s_and_b32 s100, s98, 3
	s_lshl_b32 s100, s100, 9
	s_mov_b32 s101, 0
	v_lshl_add_u64 v[106:107], v[106:107], 0, s[100:101]
	v_lshl_add_u64 v[106:107], v[106:107], 0, v[64:65]
	global_load_dwordx4 v[200:203], v[106:107], off
	global_load_dwordx4 v[204:207], v[106:107], off offset:16
	global_load_dwordx4 v[208:211], v[106:107], off offset:32
	global_load_dwordx4 v[212:215], v[106:107], off offset:48
	s_lshl_b32 s100, s98, 16
	v_lshl_add_u64 v[108:109], v[66:67], 0, s[100:101]
	v_readfirstlane_b32 s100, v178
	s_nop 1
	s_lshr_b32 s100, s100, 6
	s_lshl_b32 s100, s100, 5
	v_or_b32_e32 v110, s100, v80
	v_lshlrev_b32_e32 v110, 8, v110
	v_mov_b32_e32 v111, v65
	v_lshl_add_u64 v[110:111], v[108:109], 0, v[110:111]
	s_movk_i32 s100, 0x1000
	v_lshl_add_u64 v[108:109], v[110:111], 0, s[100:101]
	global_load_dwordx4 v[216:219], v[110:111], off
	global_load_dwordx4 v[220:223], v[110:111], off offset:64
	global_load_dwordx4 v[224:227], v[108:109], off
	global_load_dwordx4 v[228:231], v[108:109], off offset:64
	global_load_dwordx4 v[232:235], v[110:111], off offset:128
	global_load_dwordx4 v[236:239], v[110:111], off offset:192
	global_load_dwordx4 v[240:243], v[108:109], off offset:128
	global_load_dwordx4 v[244:247], v[108:109], off offset:192
	s_lshl_b32 s100, s99, 6
	v_lshl_add_u64 v[106:107], v[68:69], 0, s[100:101]
	global_load_dwordx4 v[248:251], v[106:107], off
	s_waitcnt vmcnt(0)
	s_branch .LBB0_728

; #define LAS __attribute__((address_space(3)))
; template <int MODE, bool dry = false>
; __device__ __forceinline__ void gla_unit(const Args& a, LAS unsigned char* lds, int idx, int h, int tid, const float (&wu)[16], float bd) {
;     ...
;     bf16x8 vraw[C / 16];
;     { const int t = tid & (C - 1), g0 = tid / C;
; #pragma unroll
;         for (int gi = 0; gi < C / 16; ++gi) vraw[gi] = *(const bf16x8*)(VB + (size_t)(row0 + t) * 1024 + h * 256 + 8 * (g0 * (C / 16) + gi)); }
;     bf16x8 sraw[4][2];
;     if (MODE == 1) {
; #pragma unroll
;         for (int ks = 0; ks < 4; ++ks)
; #pragma unroll
;             for (int m = 0; m < 2; ++m) sraw[ks][m] = *(const bf16x8*)(US + (size_t)(32 * wave + 16 * m + fr) * 128 + 32 * ks + 8 * kq); }
;     LAS f32x4* dlrL = (LAS f32x4*)(lds + G_DLR);
;     if (tid < C * 4) dlrL[tid] = ((const f32x4*)(DLR + (size_t)row0 * 16))[tid];
;     __syncthreads();
;     {
;         const int dk = tid & 127, tq = wave >> 1, col = h * 128 + dk;
;         bf16_t kraw[TPT], qraw[TPT];
; #pragma unroll
;         for (int i = 0; i < TPT; ++i) { const size_t gi = (size_t)(row0 + tq * TPT + i) * 512 + col; kraw[i] = KB[gi]; qraw[i] = (MODE != 0) ? QB[gi] : (bf16_t)0; }
;         float bl[TPT]; float run = 0.f;
; #pragma unroll
;         for (int i = 0; i < TPT; ++i) { const LAS f32x4* dp = dlrL + (tq * TPT + i) * 4; float z = bd;
; #pragma unroll
;             for (int j4 = 0; j4 < 4; ++j4) { const f32x4 d = dp[j4]; z += d[0] * wu[4 * j4] + d[1] * wu[4 * j4 + 1] + d[2] * wu[4 * j4 + 2] + d[3] * wu[4 * j4 + 3]; }
;             const float la = (fminf(z, 0.f) - __logf(1.f + __expf(-fabsf(z)))) * (1.f / 16.f);
.LBB0_730:
	s_lshl_b32 s65, s44, 4
	s_and_b32 s46, s65, 0xffffffc0
	s_and_b32 s66, s44, 3
	v_readfirstlane_b32 s67, v178
	s_ashr_i32 s45, s44, 31
	s_nop 0
	s_lshr_b32 s8, s67, 6
	s_lshl_b32 s20, s8, 5
	v_or_b32_e32 v72, s20, v80
	v_mov_b32_e32 v73, v65
	s_waitcnt vmcnt(8)
	v_mov_b64_e32 v[60:61], v[200:201]
	v_mov_b64_e32 v[62:63], v[202:203]
	v_mov_b64_e32 v[56:57], v[204:205]
	v_mov_b64_e32 v[58:59], v[206:207]
	v_mov_b64_e32 v[52:53], v[208:209]
	v_mov_b64_e32 v[54:55], v[210:211]
	v_mov_b64_e32 v[48:49], v[212:213]
	v_mov_b64_e32 v[50:51], v[214:215]
	v_mov_b64_e32 v[40:41], v[216:217]
	v_mov_b64_e32 v[42:43], v[218:219]
	v_mov_b64_e32 v[32:33], v[220:221]
	v_mov_b64_e32 v[34:35], v[222:223]
	v_mov_b64_e32 v[44:45], v[224:225]
	v_mov_b64_e32 v[46:47], v[226:227]
	v_mov_b64_e32 v[36:37], v[228:229]
	v_mov_b64_e32 v[38:39], v[230:231]
	v_mov_b64_e32 v[24:25], v[232:233]
	v_mov_b64_e32 v[26:27], v[234:235]
	v_mov_b64_e32 v[20:21], v[236:237]
	v_mov_b64_e32 v[22:23], v[238:239]
	v_mov_b64_e32 v[28:29], v[240:241]
	v_mov_b64_e32 v[30:31], v[242:243]
	v_mov_b64_e32 v[16:17], v[244:245]
	v_mov_b64_e32 v[18:19], v[246:247]
	s_and_saveexec_b64 s[6:7], s[0:1]
	s_cbranch_execz .LBB0_732
	s_ashr_i32 s47, s46, 31
	ds_write_b128 v81, v[248:251]
.LBB0_732:
	s_or_b64 exec, exec, s[6:7]
	s_lshr_b32 s9, s67, 7
	s_lshl_b32 s3, s9, 10
	s_add_i32 s3, s3, 0
	s_add_i32 s3, s3, 0x19800
	v_mov_b32_e32 v113, s3
	s_waitcnt lgkmcnt(0)
	s_add_i32 s98, s44, s58
	s_cmpk_lt_i32 s98, 0x400
	s_cbranch_scc0 .Lp4pf_skip
	s_lshl_b32 s99, s98, 4
	s_and_b32 s99, s99, 0xffffffc0
	v_or_b32_e32 v106, s99, v176
	v_mov_b32_e32 v107, v65
	v_lshlrev_b64 v[106:107], 11, v[106:107]
	v_lshl_add_u64 v[106:107], s[28:29], 0, v[106:107]
	s_and_b32 s100, s98, 3
	s_lshl_b32 s100, s100, 9
	s_mov_b32 s101, 0
	v_lshl_add_u64 v[106:107], v[106:107], 0, s[100:101]
	v_lshl_add_u64 v[106:107], v[106:107], 0, v[64:65]
	global_load_dwordx4 v[200:203], v[106:107], off
	global_load_dwordx4 v[204:207], v[106:107], off offset:16
	global_load_dwordx4 v[208:211], v[106:107], off offset:32
	global_load_dwordx4 v[212:215], v[106:107], off offset:48
	s_lshl_b32 s100, s98, 16
	v_lshl_add_u64 v[108:109], v[66:67], 0, s[100:101]
	v_readfirstlane_b32 s100, v178
	s_nop 1
	s_lshr_b32 s100, s100, 6
	s_lshl_b32 s100, s100, 5
	v_or_b32_e32 v110, s100, v80
	v_lshlrev_b32_e32 v110, 8, v110
	v_mov_b32_e32 v111, v65
	v_lshl_add_u64 v[110:111], v[108:109], 0, v[110:111]
	s_movk_i32 s100, 0x1000
	v_lshl_add_u64 v[108:109], v[110:111], 0, s[100:101]
	global_load_dwordx4 v[216:219], v[110:111], off
	global_load_dwordx4 v[220:223], v[110:111], off offset:64
	global_load_dwordx4 v[224:227], v[108:109], off
	global_load_dwordx4 v[228:231], v[108:109], off offset:64
	global_load_dwordx4 v[232:235], v[110:111], off offset:128
	global_load_dwordx4 v[236:239], v[110:111], off offset:192
	global_load_dwordx4 v[240:243], v[108:109], off offset:128
	global_load_dwordx4 v[244:247], v[108:109], off offset:192
	s_lshl_b32 s100, s99, 6
	v_lshl_add_u64 v[106:107], v[68:69], 0, s[100:101]
	global_load_dwordx4 v[248:251], v[106:107], off
.Lp4pf_skip:
	s_barrier
	ds_read_b128 v[102:105], v113
	ds_read_b128 v[106:109], v113 offset:16
	s_and_b32 s3, s44, 0xffffffc
	s_add_i32 s3, s9, s3
	s_lshl_b32 s6, s3, 4
	s_waitcnt lgkmcnt(1)
	v_mul_f32_e32 v73, v1, v103
	s_waitcnt lgkmcnt(0)
	v_mul_f32_e32 v75, v5, v107
	v_fmac_f32_e32 v73, v0, v102
	v_fmac_f32_e32 v75, v4, v106
	v_fmac_f32_e32 v73, v2, v104
	v_fmac_f32_e32 v75, v6, v108
	v_fmac_f32_e32 v73, v3, v105
	v_fmac_f32_e32 v75, v7, v109
	ds_read_b128 v[102:105], v113 offset:32
	ds_read_b128 v[106:109], v113 offset:48
	s_ashr_i32 s7, s6, 31
	s_lshl_b64 s[10:11], s[6:7], 10
	v_add_f32_e32 v73, v74, v73
	s_waitcnt lgkmcnt(1)
	v_mul_f32_e32 v76, v9, v103
	s_waitcnt lgkmcnt(0)
	v_mul_f32_e32 v77, v13, v107
	v_fmac_f32_e32 v76, v8, v102
	v_fmac_f32_e32 v77, v12, v106
	v_fmac_f32_e32 v76, v10, v104
	v_fmac_f32_e32 v77, v14, v108
	v_fmac_f32_e32 v76, v11, v105
	v_fmac_f32_e32 v77, v15, v109
	ds_read_b128 v[102:105], v113 offset:64
	ds_read_b128 v[106:109], v113 offset:80
	v_add_f32_e32 v73, v73, v75
	v_add_f32_e32 v73, v73, v76
	v_add_f32_e32 v73, v73, v77
	s_waitcnt lgkmcnt(1)
	v_mul_f32_e32 v101, v1, v103
	v_fmac_f32_e32 v101, v0, v102
	s_waitcnt lgkmcnt(0)
	v_mul_f32_e32 v102, v5, v107
	v_fmac_f32_e32 v102, v4, v106
	v_fmac_f32_e32 v101, v2, v104
	v_fmac_f32_e32 v102, v6, v108
	v_fmac_f32_e32 v101, v3, v105
	v_fmac_f32_e32 v102, v7, v109
	ds_read_b128 v[104:107], v113 offset:96
	ds_read_b128 v[108:111], v113 offset:112
	v_mul_f32_e64 v75, |v73|, s60
	v_exp_f32_e32 v75, v75
	v_min_f32_e32 v73, 0, v73
	s_waitcnt lgkmcnt(1)
	v_mul_f32_e32 v103, v9, v105
	v_fmac_f32_e32 v103, v8, v104
	v_fmac_f32_e32 v103, v10, v106
	s_waitcnt lgkmcnt(0)
	v_mul_f32_e32 v104, v13, v109
	v_fmac_f32_e32 v103, v11, v107
	v_fmac_f32_e32 v104, v12, v108
	ds_read_b128 v[106:109], v113 offset:128
	ds_read_b128 v[114:117], v113 offset:144
	v_fmac_f32_e32 v104, v14, v110
	v_fmac_f32_e32 v104, v15, v111
	v_add_f32_e32 v75, 1.0, v75
	s_waitcnt lgkmcnt(1)
	v_mul_f32_e32 v105, v1, v107
	v_fmac_f32_e32 v105, v0, v106
	s_waitcnt lgkmcnt(0)
	v_mul_f32_e32 v106, v5, v115
	v_fmac_f32_e32 v106, v4, v114
	v_fmac_f32_e32 v105, v2, v108
	v_fmac_f32_e32 v106, v6, v116
	v_fmac_f32_e32 v105, v3, v109
	v_fmac_f32_e32 v106, v7, v117
	ds_read_b128 v[108:111], v113 offset:160
	ds_read_b128 v[114:117], v113 offset:176
	v_cmp_gt_f32_e32 vcc, s61, v75
	s_and_b32 s3, s67, 0x3fffff80
	s_waitcnt lgkmcnt(1)
	v_mul_f32_e32 v107, v9, v109
	v_fmac_f32_e32 v107, v8, v108
	s_waitcnt lgkmcnt(0)
; #define LAS __attribute__((address_space(3)))
; template <int MODE, bool dry = false>
; __device__ __forceinline__ void gla_unit(const Args& a, LAS unsigned char* lds, int idx, int h, int tid, const float (&wu)[16], float bd) {
;     ...
;         for (int i = 0; i < TPT; ++i) { const LAS f32x4* dp = dlrL + (tq * TPT + i) * 4; float z = bd;
; #pragma unroll
;             for (int j4 = 0; j4 < 4; ++j4) { const f32x4 d = dp[j4]; z += d[0] * wu[4 * j4] + d[1] * wu[4 * j4 + 1] + d[2] * wu[4 * j4 + 2] + d[3] * wu[4 * j4 + 3]; }
;             const float la = (fminf(z, 0.f) - __logf(1.f + __expf(-fabsf(z)))) * (1.f / 16.f);
	v_mul_f32_e32 v108, v13, v115
	v_fmac_f32_e32 v108, v12, v114
	v_fmac_f32_e32 v108, v14, v116
	v_fmac_f32_e32 v108, v15, v117
	ds_read_b128 v[114:117], v113 offset:192
	ds_read_b128 v[118:121], v113 offset:208
	v_fmac_f32_e32 v107, v10, v110
	v_fmac_f32_e32 v107, v11, v111
	v_cndmask_b32_e64 v76, 0, 32, vcc
	s_waitcnt lgkmcnt(1)
	v_mul_f32_e32 v109, v1, v115
	s_waitcnt lgkmcnt(0)
	v_mul_f32_e32 v110, v5, v119
	v_fmac_f32_e32 v109, v0, v114
	v_fmac_f32_e32 v110, v4, v118
	v_fmac_f32_e32 v109, v2, v116
	v_fmac_f32_e32 v110, v6, v120
	v_fmac_f32_e32 v109, v3, v117
	v_fmac_f32_e32 v110, v7, v121
	ds_read_b128 v[114:117], v113 offset:224
	ds_read_b128 v[118:121], v113 offset:240
	v_ldexp_f32 v75, v75, v76
	v_log_f32_e32 v75, v75
	s_waitcnt lgkmcnt(1)
	v_mul_f32_e32 v111, v9, v115
	s_waitcnt lgkmcnt(0)
	v_mul_f32_e32 v112, v13, v119
	v_fmac_f32_e32 v111, v8, v114
	v_fmac_f32_e32 v112, v12, v118
	v_fmac_f32_e32 v111, v10, v116
	v_fmac_f32_e32 v112, v14, v120
	v_fmac_f32_e32 v111, v11, v117
	v_fmac_f32_e32 v112, v15, v121
	ds_read_b128 v[116:119], v113 offset:256
	ds_read_b128 v[120:123], v113 offset:272
	v_mul_f32_e32 v76, 0x3f317217, v75
	v_fma_f32 v76, v75, s62, -v76
	v_fmac_f32_e32 v76, 0x3377d1cf, v75
	s_waitcnt lgkmcnt(1)
	v_mul_f32_e32 v114, v1, v117
	s_waitcnt lgkmcnt(0)
	v_mul_f32_e32 v115, v5, v121
	v_fmac_f32_e32 v114, v0, v116
	v_fmac_f32_e32 v115, v4, v120
	v_fmac_f32_e32 v114, v2, v118
	v_fmac_f32_e32 v115, v6, v122
	v_fmac_f32_e32 v114, v3, v119
	v_fmac_f32_e32 v115, v7, v123
	ds_read_b128 v[118:121], v113 offset:288
	ds_read_b128 v[122:125], v113 offset:304
	v_fmac_f32_e32 v76, 0x3f317217, v75
	s_waitcnt lgkmcnt(1)
	v_mul_f32_e32 v116, v9, v119
	s_waitcnt lgkmcnt(0)
	v_mul_f32_e32 v117, v13, v123
	v_fmac_f32_e32 v116, v8, v118
	v_fmac_f32_e32 v117, v12, v122
	v_fmac_f32_e32 v116, v10, v120
	v_fmac_f32_e32 v117, v14, v124
	v_fmac_f32_e32 v116, v11, v121
	v_fmac_f32_e32 v117, v15, v125
	ds_read_b128 v[120:123], v113 offset:320
	ds_read_b128 v[124:127], v113 offset:336
	s_waitcnt lgkmcnt(1)
	v_mul_f32_e32 v118, v1, v121
	s_waitcnt lgkmcnt(0)
	v_mul_f32_e32 v119, v5, v125
	v_fmac_f32_e32 v118, v0, v120
	v_fmac_f32_e32 v119, v4, v124
	v_fmac_f32_e32 v118, v2, v122
	v_fmac_f32_e32 v119, v6, v126
	v_fmac_f32_e32 v118, v3, v123
	v_fmac_f32_e32 v119, v7, v127
	ds_read_b128 v[122:125], v113 offset:352
	ds_read_b128 v[126:129], v113 offset:368
	s_waitcnt lgkmcnt(1)
	v_mul_f32_e32 v120, v9, v123
	s_waitcnt lgkmcnt(0)
	v_mul_f32_e32 v121, v13, v127
	v_fmac_f32_e32 v120, v8, v122
	v_fmac_f32_e32 v121, v12, v126
	v_fmac_f32_e32 v120, v10, v124
	v_fmac_f32_e32 v121, v14, v128
	v_fmac_f32_e32 v120, v11, v125
	v_fmac_f32_e32 v121, v15, v129
	ds_read_b128 v[124:127], v113 offset:384
	ds_read_b128 v[128:131], v113 offset:400
	s_waitcnt lgkmcnt(1)
	v_mul_f32_e32 v122, v1, v125
	s_waitcnt lgkmcnt(0)
	v_mul_f32_e32 v123, v5, v129
	v_fmac_f32_e32 v122, v0, v124
	v_fmac_f32_e32 v123, v4, v128
	v_fmac_f32_e32 v122, v2, v126
	v_fmac_f32_e32 v123, v6, v130
	v_fmac_f32_e32 v122, v3, v127
	v_fmac_f32_e32 v123, v7, v131
	ds_read_b128 v[126:129], v113 offset:416
	ds_read_b128 v[130:133], v113 offset:432
	s_waitcnt lgkmcnt(1)
	v_mul_f32_e32 v124, v9, v127
	s_waitcnt lgkmcnt(0)
	v_mul_f32_e32 v125, v13, v131
	v_fmac_f32_e32 v124, v8, v126
	v_fmac_f32_e32 v125, v12, v130
	v_fmac_f32_e32 v124, v10, v128
	v_fmac_f32_e32 v125, v14, v132
	v_fmac_f32_e32 v124, v11, v129
	v_fmac_f32_e32 v125, v15, v133
	ds_read_b128 v[128:131], v113 offset:448
	ds_read_b128 v[132:135], v113 offset:464
	s_waitcnt lgkmcnt(1)
	v_mul_f32_e32 v126, v1, v129
	s_waitcnt lgkmcnt(0)
	v_mul_f32_e32 v127, v5, v133
	v_fmac_f32_e32 v126, v0, v128
	v_fmac_f32_e32 v127, v4, v132
	v_fmac_f32_e32 v126, v2, v130
	v_fmac_f32_e32 v127, v6, v134
	v_fmac_f32_e32 v126, v3, v131
	v_fmac_f32_e32 v127, v7, v135
	ds_read_b128 v[130:133], v113 offset:480
	ds_read_b128 v[134:137], v113 offset:496
	s_waitcnt lgkmcnt(1)
	v_mul_f32_e32 v128, v9, v131
	s_waitcnt lgkmcnt(0)
	v_mul_f32_e32 v129, v13, v135
	v_fmac_f32_e32 v128, v8, v130
	v_fmac_f32_e32 v129, v12, v134
	v_fmac_f32_e32 v128, v10, v132
	v_fmac_f32_e32 v129, v14, v136
	v_fmac_f32_e32 v128, v11, v133
	v_fmac_f32_e32 v129, v15, v137
	ds_read_b128 v[132:135], v113 offset:512
	ds_read_b128 v[136:139], v113 offset:528
	s_waitcnt lgkmcnt(1)
	v_mul_f32_e32 v130, v1, v133
	s_waitcnt lgkmcnt(0)
	v_mul_f32_e32 v131, v5, v137
	v_fmac_f32_e32 v130, v0, v132
	v_fmac_f32_e32 v131, v4, v136
	v_fmac_f32_e32 v130, v2, v134
	v_fmac_f32_e32 v131, v6, v138
	v_fmac_f32_e32 v130, v3, v135
	v_fmac_f32_e32 v131, v7, v139
	ds_read_b128 v[134:137], v113 offset:544
	ds_read_b128 v[138:141], v113 offset:560
	s_waitcnt lgkmcnt(1)
	v_mul_f32_e32 v132, v9, v135
	s_waitcnt lgkmcnt(0)
	v_mul_f32_e32 v133, v13, v139
	v_fmac_f32_e32 v132, v8, v134
	v_fmac_f32_e32 v133, v12, v138
	v_fmac_f32_e32 v132, v10, v136
	v_fmac_f32_e32 v133, v14, v140
	v_fmac_f32_e32 v132, v11, v137
	v_fmac_f32_e32 v133, v15, v141
	ds_read_b128 v[136:139], v113 offset:576
	ds_read_b128 v[140:143], v113 offset:592
	s_waitcnt lgkmcnt(1)
	v_mul_f32_e32 v134, v1, v137
	s_waitcnt lgkmcnt(0)
	v_mul_f32_e32 v135, v5, v141
	v_fmac_f32_e32 v134, v0, v136
	v_fmac_f32_e32 v135, v4, v140
	v_fmac_f32_e32 v134, v2, v138
	v_fmac_f32_e32 v135, v6, v142
	v_fmac_f32_e32 v134, v3, v139
	v_fmac_f32_e32 v135, v7, v143
	ds_read_b128 v[138:141], v113 offset:608
	ds_read_b128 v[142:145], v113 offset:624
	s_waitcnt lgkmcnt(1)
	v_mul_f32_e32 v136, v9, v139
	s_waitcnt lgkmcnt(0)
	v_mul_f32_e32 v137, v13, v143
	v_fmac_f32_e32 v136, v8, v138
	v_fmac_f32_e32 v137, v12, v142
	v_fmac_f32_e32 v136, v10, v140
	v_fmac_f32_e32 v137, v14, v144
	v_fmac_f32_e32 v136, v11, v141
	v_fmac_f32_e32 v137, v15, v145
	ds_read_b128 v[140:143], v113 offset:640
	ds_read_b128 v[144:147], v113 offset:656
	s_waitcnt lgkmcnt(1)
; #define LAS __attribute__((address_space(3)))
; template <int MODE, bool dry = false>
; __device__ __forceinline__ void gla_unit(const Args& a, LAS unsigned char* lds, int idx, int h, int tid, const float (&wu)[16], float bd) {
;     ...
;         for (int i = 0; i < TPT; ++i) { const size_t gi = (size_t)(row0 + tq * TPT + i) * 512 + col; kraw[i] = KB[gi]; qraw[i] = (MODE != 0) ? QB[gi] : (bf16_t)0; }
;         float bl[TPT]; float run = 0.f;
; #pragma unroll
;         for (int i = 0; i < TPT; ++i) { const LAS f32x4* dp = dlrL + (tq * TPT + i) * 4; float z = bd;
; #pragma unroll
;             for (int j4 = 0; j4 < 4; ++j4) { const f32x4 d = dp[j4]; z += d[0] * wu[4 * j4] + d[1] * wu[4 * j4 + 1] + d[2] * wu[4 * j4 + 2] + d[3] * wu[4 * j4 + 3]; }
;             const float la = (fminf(z, 0.f) - __logf(1.f + __expf(-fabsf(z)))) * (1.f / 16.f);
	v_mul_f32_e32 v138, v1, v141
	s_waitcnt lgkmcnt(0)
	v_mul_f32_e32 v139, v5, v145
	v_fmac_f32_e32 v138, v0, v140
	v_fmac_f32_e32 v139, v4, v144
	v_fmac_f32_e32 v138, v2, v142
	v_fmac_f32_e32 v139, v6, v146
	v_fmac_f32_e32 v138, v3, v143
	v_fmac_f32_e32 v139, v7, v147
	ds_read_b128 v[142:145], v113 offset:672
	ds_read_b128 v[146:149], v113 offset:688
	s_waitcnt lgkmcnt(1)
	v_mul_f32_e32 v140, v9, v143
	s_waitcnt lgkmcnt(0)
	v_mul_f32_e32 v141, v13, v147
	v_fmac_f32_e32 v140, v8, v142
	v_fmac_f32_e32 v141, v12, v146
	v_fmac_f32_e32 v140, v10, v144
	v_fmac_f32_e32 v141, v14, v148
	v_fmac_f32_e32 v140, v11, v145
	v_fmac_f32_e32 v141, v15, v149
	ds_read_b128 v[144:147], v113 offset:704
	ds_read_b128 v[148:151], v113 offset:720
	s_waitcnt lgkmcnt(1)
	v_mul_f32_e32 v142, v1, v145
	s_waitcnt lgkmcnt(0)
	v_mul_f32_e32 v143, v5, v149
	v_fmac_f32_e32 v142, v0, v144
	v_fmac_f32_e32 v143, v4, v148
	v_fmac_f32_e32 v142, v2, v146
	v_fmac_f32_e32 v143, v6, v150
	v_fmac_f32_e32 v142, v3, v147
	v_fmac_f32_e32 v143, v7, v151
	ds_read_b128 v[146:149], v113 offset:736
	ds_read_b128 v[150:153], v113 offset:752
	v_mov_b32_e32 v145, s11
	s_waitcnt lgkmcnt(1)
	v_mul_f32_e32 v147, v9, v147
	v_fmac_f32_e32 v147, v8, v146
	v_fmac_f32_e32 v147, v10, v148
	s_waitcnt lgkmcnt(0)
	v_mul_f32_e32 v148, v13, v151
	v_fmac_f32_e32 v148, v12, v150
	v_fmac_f32_e32 v148, v14, v152
	v_fmac_f32_e32 v148, v15, v153
	ds_read_b128 v[150:153], v113 offset:768
	ds_read_b128 v[158:161], v113 offset:784
	v_fmac_f32_e32 v147, v11, v149
	s_waitcnt lgkmcnt(1)
	v_mul_f32_e32 v155, v1, v151
	v_fmac_f32_e32 v155, v0, v150
	v_fmac_f32_e32 v155, v2, v152
	v_fmac_f32_e32 v155, v3, v153
	ds_read_b128 v[150:153], v113 offset:800
	ds_read_b128 v[166:169], v113 offset:816
	s_waitcnt lgkmcnt(2)
	v_mul_f32_e32 v156, v5, v159
	v_fmac_f32_e32 v156, v4, v158
	v_fmac_f32_e32 v156, v6, v160
	v_fmac_f32_e32 v156, v7, v161
	s_waitcnt lgkmcnt(1)
	v_mul_f32_e32 v161, v9, v151
	v_fmac_f32_e32 v161, v8, v150
	v_fmac_f32_e32 v161, v10, v152
	v_fmac_f32_e32 v161, v11, v153
	ds_read_b128 v[150:153], v113 offset:832
	ds_read_b128 v[170:173], v113 offset:848
	s_waitcnt lgkmcnt(2)
	v_mul_f32_e32 v164, v13, v167
	v_fmac_f32_e32 v164, v12, v166
	v_fmac_f32_e32 v164, v14, v168
	v_fmac_f32_e32 v164, v15, v169
	s_waitcnt lgkmcnt(1)
	v_mul_f32_e32 v169, v1, v151
	s_waitcnt lgkmcnt(0)
	v_mul_f32_e32 v171, v5, v171
	v_fmac_f32_e32 v169, v0, v150
	v_fmac_f32_e32 v171, v4, v170
	v_fmac_f32_e32 v169, v2, v152
	v_fmac_f32_e32 v171, v6, v172
	v_fmac_f32_e32 v169, v3, v153
	v_fmac_f32_e32 v171, v7, v173
	ds_read_b128 v[150:153], v113 offset:864
	ds_read_b128 v[172:175], v113 offset:880
	s_waitcnt lgkmcnt(1)
	v_mul_f32_e32 v179, v9, v151
	s_waitcnt lgkmcnt(0)
	v_mul_f32_e32 v180, v13, v173
	v_fmac_f32_e32 v179, v8, v150
	v_fmac_f32_e32 v180, v12, v172
	v_fmac_f32_e32 v179, v10, v152
	v_fmac_f32_e32 v180, v14, v174
	v_fmac_f32_e32 v179, v11, v153
	v_fmac_f32_e32 v180, v15, v175
	ds_read_b128 v[150:153], v113 offset:896
	ds_read_b128 v[172:175], v113 offset:912
	s_waitcnt lgkmcnt(1)
	v_mul_f32_e32 v185, v1, v151
	s_waitcnt lgkmcnt(0)
	v_mul_f32_e32 v188, v5, v173
	v_fmac_f32_e32 v185, v0, v150
	v_fmac_f32_e32 v188, v4, v172
	v_fmac_f32_e32 v185, v2, v152
	v_fmac_f32_e32 v188, v6, v174
	v_fmac_f32_e32 v185, v3, v153
	v_fmac_f32_e32 v188, v7, v175
	ds_read_b128 v[150:153], v113 offset:928
	ds_read_b128 v[172:175], v113 offset:944
	s_waitcnt lgkmcnt(1)
	v_mul_f32_e32 v189, v9, v151
	s_waitcnt lgkmcnt(0)
	v_mul_f32_e32 v190, v13, v173
	v_fmac_f32_e32 v189, v8, v150
	v_fmac_f32_e32 v190, v12, v172
	v_fmac_f32_e32 v189, v10, v152
	v_fmac_f32_e32 v190, v14, v174
	v_fmac_f32_e32 v189, v11, v153
	v_fmac_f32_e32 v190, v15, v175
	ds_read_b128 v[150:153], v113 offset:960
	ds_read_b128 v[172:175], v113 offset:976
	s_waitcnt lgkmcnt(1)
	v_mul_f32_e32 v191, v1, v151
	s_waitcnt lgkmcnt(0)
	v_mul_f32_e32 v196, v5, v173
	v_fmac_f32_e32 v191, v0, v150
	v_fmac_f32_e32 v196, v4, v172
	v_fmac_f32_e32 v191, v2, v152
	v_fmac_f32_e32 v196, v6, v174
	v_fmac_f32_e32 v191, v3, v153
	v_fmac_f32_e32 v196, v7, v175
	ds_read_b128 v[150:153], v113 offset:992
	ds_read_b128 v[172:175], v113 offset:1008
	v_lshlrev_b32_e32 v113, 1, v71
	v_lshl_or_b32 v113, s66, 8, v113
	v_or_b32_e32 v144, s10, v113
	s_or_b32 s10, s6, 1
	s_waitcnt lgkmcnt(1)
	v_mul_f32_e32 v197, v9, v151
	s_ashr_i32 s11, s10, 31
	v_fmac_f32_e32 v197, v8, v150
	v_lshl_add_u64 v[150:151], s[30:31], 0, v[144:145]
	v_lshl_add_u64 v[144:145], s[26:27], 0, v[144:145]
	s_lshl_b64 s[10:11], s[10:11], 10
	global_load_ushort v186, v[150:151], off
	global_load_ushort v187, v[144:145], off
	v_or_b32_e32 v144, s10, v113
	s_or_b32 s10, s6, 2
	v_mov_b32_e32 v145, s11
	s_ashr_i32 s11, s10, 31
	v_lshl_add_u64 v[150:151], s[30:31], 0, v[144:145]
	v_lshl_add_u64 v[144:145], s[26:27], 0, v[144:145]
	s_lshl_b64 s[10:11], s[10:11], 10
	global_load_ushort v184, v[150:151], off
	global_load_ushort v183, v[144:145], off
	v_or_b32_e32 v144, s10, v113
	s_or_b32 s10, s6, 3
	v_mov_b32_e32 v145, s11
	s_ashr_i32 s11, s10, 31
	v_lshl_add_u64 v[150:151], s[30:31], 0, v[144:145]
	v_lshl_add_u64 v[144:145], s[26:27], 0, v[144:145]
	s_lshl_b64 s[10:11], s[10:11], 10
	s_waitcnt lgkmcnt(0)
; #define LAS __attribute__((address_space(3)))
; template <int MODE, bool dry = false>
; __device__ __forceinline__ void gla_unit(const Args& a, LAS unsigned char* lds, int idx, int h, int tid, const float (&wu)[16], float bd) {
;     ...
;         for (int i = 0; i < TPT; ++i) { const size_t gi = (size_t)(row0 + tq * TPT + i) * 512 + col; kraw[i] = KB[gi]; qraw[i] = (MODE != 0) ? QB[gi] : (bf16_t)0; }
;         float bl[TPT]; float run = 0.f;
; #pragma unroll
;         for (int i = 0; i < TPT; ++i) { const LAS f32x4* dp = dlrL + (tq * TPT + i) * 4; float z = bd;
; #pragma unroll
;             for (int j4 = 0; j4 < 4; ++j4) { const f32x4 d = dp[j4]; z += d[0] * wu[4 * j4] + d[1] * wu[4 * j4 + 1] + d[2] * wu[4 * j4 + 2] + d[3] * wu[4 * j4 + 3]; }
;             const float la = (fminf(z, 0.f) - __logf(1.f + __expf(-fabsf(z)))) * (1.f / 16.f);
;             run += la; bl[i] = run; }
	v_mul_f32_e32 v198, v13, v173
	global_load_ushort v182, v[150:151], off
	global_load_ushort v181, v[144:145], off
	v_or_b32_e32 v144, s10, v113
	s_or_b32 s10, s6, 4
	v_fmac_f32_e32 v198, v12, v172
	v_mov_b32_e32 v145, s11
	s_ashr_i32 s11, s10, 31
	v_fmac_f32_e32 v198, v14, v174
	v_lshl_add_u64 v[150:151], s[30:31], 0, v[144:145]
	v_lshl_add_u64 v[144:145], s[26:27], 0, v[144:145]
	s_lshl_b64 s[10:11], s[10:11], 10
	v_fmac_f32_e32 v198, v15, v175
	global_load_ushort v177, v[150:151], off
	global_load_ushort v175, v[144:145], off
	v_or_b32_e32 v144, s10, v113
	s_or_b32 s10, s6, 5
	v_mov_b32_e32 v145, s11
	s_ashr_i32 s11, s10, 31
	v_lshl_add_u64 v[150:151], s[30:31], 0, v[144:145]
	v_lshl_add_u64 v[144:145], s[26:27], 0, v[144:145]
	s_lshl_b64 s[10:11], s[10:11], 10
	global_load_ushort v174, v[150:151], off
	global_load_ushort v173, v[144:145], off
	v_or_b32_e32 v144, s10, v113
	s_or_b32 s10, s6, 6
	v_mov_b32_e32 v145, s11
	s_ashr_i32 s11, s10, 31
	v_lshl_add_u64 v[150:151], s[30:31], 0, v[144:145]
	v_lshl_add_u64 v[144:145], s[26:27], 0, v[144:145]
	s_lshl_b64 s[10:11], s[10:11], 10
	global_load_ushort v172, v[150:151], off
	global_load_ushort v170, v[144:145], off
	v_or_b32_e32 v144, s10, v113
	s_or_b32 s10, s6, 7
	v_mov_b32_e32 v145, s11
	s_ashr_i32 s11, s10, 31
	v_lshl_add_u64 v[150:151], s[30:31], 0, v[144:145]
	v_lshl_add_u64 v[144:145], s[26:27], 0, v[144:145]
	s_lshl_b64 s[10:11], s[10:11], 10
	global_load_ushort v168, v[150:151], off
	global_load_ushort v167, v[144:145], off
	v_or_b32_e32 v144, s10, v113
	s_or_b32 s10, s6, 8
	v_mov_b32_e32 v145, s11
	s_ashr_i32 s11, s10, 31
	v_lshl_add_u64 v[150:151], s[30:31], 0, v[144:145]
	v_lshl_add_u64 v[144:145], s[26:27], 0, v[144:145]
	s_lshl_b64 s[10:11], s[10:11], 10
	global_load_ushort v166, v[150:151], off
	global_load_ushort v165, v[144:145], off
	v_or_b32_e32 v144, s10, v113
	s_or_b32 s10, s6, 9
	v_mov_b32_e32 v145, s11
	s_ashr_i32 s11, s10, 31
	v_lshl_add_u64 v[150:151], s[30:31], 0, v[144:145]
	v_lshl_add_u64 v[144:145], s[26:27], 0, v[144:145]
	s_lshl_b64 s[10:11], s[10:11], 10
	global_load_ushort v163, v[150:151], off
	global_load_ushort v162, v[144:145], off
	v_or_b32_e32 v144, s10, v113
	s_or_b32 s10, s6, 10
	v_mov_b32_e32 v145, s11
	s_ashr_i32 s11, s10, 31
	v_lshl_add_u64 v[150:151], s[30:31], 0, v[144:145]
	v_lshl_add_u64 v[144:145], s[26:27], 0, v[144:145]
	s_lshl_b64 s[10:11], s[10:11], 10
	global_load_ushort v160, v[150:151], off
	global_load_ushort v159, v[144:145], off
	v_or_b32_e32 v144, s10, v113
	s_or_b32 s10, s6, 11
	v_mov_b32_e32 v145, s11
	s_ashr_i32 s11, s10, 31
	v_lshl_add_u64 v[150:151], s[30:31], 0, v[144:145]
	v_lshl_add_u64 v[144:145], s[26:27], 0, v[144:145]
	s_lshl_b64 s[10:11], s[10:11], 10
	global_load_ushort v158, v[150:151], off
	global_load_ushort v157, v[144:145], off
	v_or_b32_e32 v144, s10, v113
	s_or_b32 s10, s6, 12
	v_mov_b32_e32 v145, s11
	s_ashr_i32 s11, s10, 31
	v_fmac_f32_e32 v197, v10, v152
	v_lshl_add_u64 v[150:151], s[30:31], 0, v[144:145]
	v_lshl_add_u64 v[144:145], s[26:27], 0, v[144:145]
	s_lshl_b64 s[10:11], s[10:11], 10
	v_fmac_f32_e32 v197, v11, v153
	global_load_ushort v154, v[150:151], off
	global_load_ushort v153, v[144:145], off
	v_or_b32_e32 v144, s10, v113
	s_or_b32 s10, s6, 13
	v_mov_b32_e32 v145, s11
	s_ashr_i32 s11, s10, 31
	v_lshl_add_u64 v[150:151], s[30:31], 0, v[144:145]
	v_lshl_add_u64 v[144:145], s[26:27], 0, v[144:145]
	s_lshl_b64 s[10:11], s[10:11], 10
	global_load_ushort v152, v[150:151], off
	s_nop 0
	global_load_ushort v151, v[144:145], off
	v_or_b32_e32 v144, s10, v113
	s_or_b32 s10, s6, 14
	v_mov_b32_e32 v145, s11
	s_ashr_i32 s11, s10, 31
	v_lshl_add_u64 v[192:193], s[30:31], 0, v[144:145]
	v_lshl_add_u64 v[144:145], s[26:27], 0, v[144:145]
	s_lshl_b64 s[10:11], s[10:11], 10
	s_or_b32 s6, s6, 15
	global_load_ushort v150, v[192:193], off
	global_load_ushort v149, v[144:145], off
	v_or_b32_e32 v144, s10, v113
	v_mov_b32_e32 v145, s11
	s_ashr_i32 s7, s6, 31
	v_lshl_add_u64 v[192:193], s[30:31], 0, v[144:145]
	v_lshl_add_u64 v[144:145], s[26:27], 0, v[144:145]
	s_lshl_b64 s[6:7], s[6:7], 10
	global_load_ushort v146, v[192:193], off
	s_cmpk_lt_u32 s67, 0x80
	global_load_ushort v145, v[144:145], off
	v_or_b32_e32 v192, s6, v113
	v_mov_b32_e32 v193, s7
	v_cmp_lt_f32_e64 s[6:7], |v75|, s63
	v_lshl_add_u64 v[194:195], s[30:31], 0, v[192:193]
	v_lshl_add_u64 v[192:193], s[26:27], 0, v[192:193]
	v_cndmask_b32_e64 v75, v75, v76, s[6:7]
	v_cndmask_b32_e32 v76, 0, v100, vcc
	v_sub_f32_e32 v75, v75, v76
	v_sub_f32_e32 v73, v73, v75
	v_add_f32_e32 v75, v74, v101
	v_add_f32_e32 v75, v75, v102
	v_add_f32_e32 v75, v75, v103
	v_add_f32_e32 v75, v75, v104
	v_mul_f32_e64 v76, |v75|, s60
	v_exp_f32_e32 v76, v76
	v_min_f32_e32 v75, 0, v75
	global_load_ushort v144, v[194:195], off
	global_load_ushort v113, v[192:193], off
	v_add_f32_e32 v76, 1.0, v76
	v_cmp_gt_f32_e32 vcc, s61, v76
	s_nop 1
	v_cndmask_b32_e64 v77, 0, 32, vcc
	v_ldexp_f32 v76, v76, v77
	v_log_f32_e32 v76, v76
	s_nop 0
	v_mul_f32_e32 v77, 0x3f317217, v76
	v_fma_f32 v77, v76, s62, -v77
	v_fmac_f32_e32 v77, 0x3377d1cf, v76
	v_fmac_f32_e32 v77, 0x3f317217, v76
	v_cmp_lt_f32_e64 s[6:7], |v76|, s63
	s_nop 1
	v_cndmask_b32_e64 v76, v76, v77, s[6:7]
	v_cndmask_b32_e32 v77, 0, v100, vcc
	v_sub_f32_e32 v76, v76, v77
	v_sub_f32_e32 v75, v75, v76
	v_add_f32_e32 v76, v74, v105
	v_add_f32_e32 v76, v76, v106
	v_add_f32_e32 v76, v76, v107
	v_add_f32_e32 v76, v76, v108
	v_mul_f32_e64 v77, |v76|, s60
	v_exp_f32_e32 v77, v77
	v_min_f32_e32 v76, 0, v76
	v_add_f32_e32 v77, 1.0, v77
	v_cmp_gt_f32_e32 vcc, s61, v77
	s_nop 1
	v_cndmask_b32_e64 v101, 0, 32, vcc
	v_ldexp_f32 v77, v77, v101
; #define LAS __attribute__((address_space(3)))
; template <int MODE, bool dry = false>
; __device__ __forceinline__ void gla_unit(const Args& a, LAS unsigned char* lds, int idx, int h, int tid, const float (&wu)[16], float bd) {
;     ...
;         for (int i = 0; i < TPT; ++i) { const LAS f32x4* dp = dlrL + (tq * TPT + i) * 4; float z = bd;
; #pragma unroll
;             for (int j4 = 0; j4 < 4; ++j4) { const f32x4 d = dp[j4]; z += d[0] * wu[4 * j4] + d[1] * wu[4 * j4 + 1] + d[2] * wu[4 * j4 + 2] + d[3] * wu[4 * j4 + 3]; }
;             const float la = (fminf(z, 0.f) - __logf(1.f + __expf(-fabsf(z)))) * (1.f / 16.f);
;             run += la; bl[i] = run; }
	v_log_f32_e32 v77, v77
	s_nop 0
	v_mul_f32_e32 v101, 0x3f317217, v77
	v_fma_f32 v101, v77, s62, -v101
	v_fmac_f32_e32 v101, 0x3377d1cf, v77
	v_fmac_f32_e32 v101, 0x3f317217, v77
	v_cmp_lt_f32_e64 s[6:7], |v77|, s63
	s_nop 1
	v_cndmask_b32_e64 v77, v77, v101, s[6:7]
	v_cndmask_b32_e32 v101, 0, v100, vcc
	v_sub_f32_e32 v77, v77, v101
	v_sub_f32_e32 v76, v76, v77
	v_add_f32_e32 v77, v74, v109
	v_add_f32_e32 v77, v77, v110
	v_add_f32_e32 v77, v77, v111
	v_add_f32_e32 v77, v77, v112
	v_mul_f32_e64 v101, |v77|, s60
	v_exp_f32_e32 v101, v101
	v_min_f32_e32 v77, 0, v77
	v_add_f32_e32 v101, 1.0, v101
	v_cmp_gt_f32_e32 vcc, s61, v101
	s_nop 1
	v_cndmask_b32_e64 v102, 0, 32, vcc
	v_ldexp_f32 v101, v101, v102
	v_log_f32_e32 v101, v101
	s_nop 0
	v_mul_f32_e32 v102, 0x3f317217, v101
	v_fma_f32 v102, v101, s62, -v102
	v_fmac_f32_e32 v102, 0x3377d1cf, v101
	v_fmac_f32_e32 v102, 0x3f317217, v101
	v_cmp_lt_f32_e64 s[6:7], |v101|, s63
	s_nop 1
	v_cndmask_b32_e64 v101, v101, v102, s[6:7]
	v_cndmask_b32_e32 v102, 0, v100, vcc
	v_sub_f32_e32 v101, v101, v102
	v_sub_f32_e32 v77, v77, v101
	v_add_f32_e32 v101, v74, v114
	v_add_f32_e32 v101, v101, v115
	v_add_f32_e32 v101, v101, v116
	v_add_f32_e32 v101, v101, v117
	v_mul_f32_e64 v102, |v101|, s60
	v_exp_f32_e32 v102, v102
	v_min_f32_e32 v101, 0, v101
	v_fma_f32 v116, v73, s64, 0
	v_fmamk_f32 v115, v75, 0x3d800000, v116
	v_add_f32_e32 v102, 1.0, v102
	v_cmp_gt_f32_e32 vcc, s61, v102
	v_fmamk_f32 v114, v76, 0x3d800000, v115
	v_fmamk_f32 v112, v77, 0x3d800000, v114
	v_cndmask_b32_e64 v103, 0, 32, vcc
	v_ldexp_f32 v102, v102, v103
	v_log_f32_e32 v102, v102
	s_nop 0
	v_mul_f32_e32 v103, 0x3f317217, v102
	v_fma_f32 v103, v102, s62, -v103
	v_fmac_f32_e32 v103, 0x3377d1cf, v102
	v_fmac_f32_e32 v103, 0x3f317217, v102
	v_cmp_lt_f32_e64 s[6:7], |v102|, s63
	s_nop 1
	v_cndmask_b32_e64 v102, v102, v103, s[6:7]
	v_cndmask_b32_e32 v103, 0, v100, vcc
	v_sub_f32_e32 v102, v102, v103
	v_sub_f32_e32 v101, v101, v102
	v_add_f32_e32 v102, v74, v118
	v_add_f32_e32 v102, v102, v119
	v_add_f32_e32 v102, v102, v120
	v_add_f32_e32 v102, v102, v121
	v_mul_f32_e64 v103, |v102|, s60
	v_exp_f32_e32 v103, v103
	v_min_f32_e32 v102, 0, v102
	v_fmamk_f32 v111, v101, 0x3d800000, v112
	v_add_f32_e32 v103, 1.0, v103
	v_cmp_gt_f32_e32 vcc, s61, v103
	s_nop 1
	v_cndmask_b32_e64 v104, 0, 32, vcc
	v_ldexp_f32 v103, v103, v104
	v_log_f32_e32 v103, v103
	s_nop 0
	v_mul_f32_e32 v104, 0x3f317217, v103
	v_fma_f32 v104, v103, s62, -v104
	v_fmac_f32_e32 v104, 0x3377d1cf, v103
	v_fmac_f32_e32 v104, 0x3f317217, v103
	v_cmp_lt_f32_e64 s[6:7], |v103|, s63
	s_nop 1
	v_cndmask_b32_e64 v103, v103, v104, s[6:7]
	v_cndmask_b32_e32 v104, 0, v100, vcc
	v_sub_f32_e32 v103, v103, v104
	v_sub_f32_e32 v102, v102, v103
	v_add_f32_e32 v103, v74, v122
	v_add_f32_e32 v103, v103, v123
	v_add_f32_e32 v103, v103, v124
	v_add_f32_e32 v103, v103, v125
	v_mul_f32_e64 v104, |v103|, s60
	v_exp_f32_e32 v104, v104
	v_min_f32_e32 v103, 0, v103
	v_fmamk_f32 v110, v102, 0x3d800000, v111
	v_add_f32_e32 v104, 1.0, v104
	v_cmp_gt_f32_e32 vcc, s61, v104
	s_nop 1
	v_cndmask_b32_e64 v105, 0, 32, vcc
	v_ldexp_f32 v104, v104, v105
	v_log_f32_e32 v104, v104
	s_nop 0
	v_mul_f32_e32 v105, 0x3f317217, v104
	v_fma_f32 v105, v104, s62, -v105
	v_fmac_f32_e32 v105, 0x3377d1cf, v104
	v_fmac_f32_e32 v105, 0x3f317217, v104
	v_cmp_lt_f32_e64 s[6:7], |v104|, s63
	s_nop 1
	v_cndmask_b32_e64 v104, v104, v105, s[6:7]
	v_cndmask_b32_e32 v105, 0, v100, vcc
	v_sub_f32_e32 v104, v104, v105
	v_sub_f32_e32 v103, v103, v104
	v_add_f32_e32 v104, v74, v126
	v_add_f32_e32 v104, v104, v127
	v_add_f32_e32 v104, v104, v128
	v_add_f32_e32 v104, v104, v129
	v_mul_f32_e64 v105, |v104|, s60
	v_exp_f32_e32 v105, v105
	v_min_f32_e32 v104, 0, v104
	v_add_f32_e32 v105, 1.0, v105
	v_cmp_gt_f32_e32 vcc, s61, v105
	s_nop 1
	v_cndmask_b32_e64 v106, 0, 32, vcc
	v_ldexp_f32 v105, v105, v106
	v_log_f32_e32 v105, v105
	s_nop 0
	v_mul_f32_e32 v106, 0x3f317217, v105
	v_fma_f32 v106, v105, s62, -v106
	v_fmac_f32_e32 v106, 0x3377d1cf, v105
	v_fmac_f32_e32 v106, 0x3f317217, v105
	v_cmp_lt_f32_e64 s[6:7], |v105|, s63
	s_nop 1
	v_cndmask_b32_e64 v105, v105, v106, s[6:7]
	v_cndmask_b32_e32 v106, 0, v100, vcc
	v_sub_f32_e32 v105, v105, v106
	v_sub_f32_e32 v104, v104, v105
	v_add_f32_e32 v105, v74, v130
	v_add_f32_e32 v105, v105, v131
	v_add_f32_e32 v105, v105, v132
	v_add_f32_e32 v105, v105, v133
	v_mul_f32_e64 v106, |v105|, s60
	v_exp_f32_e32 v106, v106
	v_min_f32_e32 v105, 0, v105
	v_add_f32_e32 v106, 1.0, v106
	v_cmp_gt_f32_e32 vcc, s61, v106
	s_nop 1
	v_cndmask_b32_e64 v107, 0, 32, vcc
	v_ldexp_f32 v106, v106, v107
	v_log_f32_e32 v106, v106
	s_nop 0
	v_mul_f32_e32 v107, 0x3f317217, v106
	v_fma_f32 v107, v106, s62, -v107
	v_fmac_f32_e32 v107, 0x3377d1cf, v106
	v_fmac_f32_e32 v107, 0x3f317217, v106
	v_cmp_lt_f32_e64 s[6:7], |v106|, s63
	s_nop 1
	v_cndmask_b32_e64 v106, v106, v107, s[6:7]
	v_cndmask_b32_e32 v107, 0, v100, vcc
	v_sub_f32_e32 v106, v106, v107
	v_sub_f32_e32 v105, v105, v106
	v_add_f32_e32 v106, v74, v134
	v_add_f32_e32 v106, v106, v135
	v_add_f32_e32 v106, v106, v136
	v_add_f32_e32 v106, v106, v137
	v_mul_f32_e64 v107, |v106|, s60
	v_exp_f32_e32 v107, v107
	v_min_f32_e32 v106, 0, v106
	v_add_f32_e32 v107, 1.0, v107
	v_cmp_gt_f32_e32 vcc, s61, v107
	s_nop 1
	v_cndmask_b32_e64 v108, 0, 32, vcc
	v_ldexp_f32 v107, v107, v108
	v_log_f32_e32 v107, v107
	s_nop 0
	v_mul_f32_e32 v108, 0x3f317217, v107
	v_fma_f32 v108, v107, s62, -v108
	v_fmac_f32_e32 v108, 0x3377d1cf, v107
	v_fmac_f32_e32 v108, 0x3f317217, v107
; template <int MODE, bool dry = false>
; __device__ __forceinline__ void gla_unit(const Args& a, LAS unsigned char* lds, int idx, int h, int tid, const float (&wu)[16], float bd) {
;     ...
;             const float la = (fminf(z, 0.f) - __logf(1.f + __expf(-fabsf(z)))) * (1.f / 16.f);
;             run += la; bl[i] = run; }
;         psum[tq * 128 + dk] = run;
;         __syncthreads();
;         float off = 0.f, tot = 0.f;
; #pragma unroll
;         for (int p = 0; p < 4; ++p) { const float v = psum[p * 128 + dk]; tot += v; if (p < tq) off += v; }
;         if (tq == 0) { dvec[dk] = __expf(tot); if (MODE == 0) ((float*)((unsigned char*)a.out + Y_DEC))[(size_t)(idx * 4 + h) * 128 + dk] = __expf(tot); }
	v_cmp_lt_f32_e64 s[6:7], |v107|, s63
	s_nop 1
	v_cndmask_b32_e64 v107, v107, v108, s[6:7]
	v_cndmask_b32_e32 v108, 0, v100, vcc
	v_sub_f32_e32 v107, v107, v108
	v_sub_f32_e32 v106, v106, v107
	v_add_f32_e32 v107, v74, v138
	v_add_f32_e32 v107, v107, v139
	v_add_f32_e32 v107, v107, v140
	v_add_f32_e32 v107, v107, v141
	v_mul_f32_e64 v108, |v107|, s60
	v_exp_f32_e32 v108, v108
	v_min_f32_e32 v107, 0, v107
	v_add_f32_e32 v108, 1.0, v108
	v_cmp_gt_f32_e32 vcc, s61, v108
	s_nop 1
	v_cndmask_b32_e64 v109, 0, 32, vcc
	v_ldexp_f32 v108, v108, v109
	v_log_f32_e32 v108, v108
	s_nop 0
	v_mul_f32_e32 v109, 0x3f317217, v108
	v_fma_f32 v109, v108, s62, -v109
	v_fmac_f32_e32 v109, 0x3377d1cf, v108
	v_fmac_f32_e32 v109, 0x3f317217, v108
	v_cmp_lt_f32_e64 s[6:7], |v108|, s63
	s_nop 1
	v_cndmask_b32_e64 v108, v108, v109, s[6:7]
	v_cndmask_b32_e32 v109, 0, v100, vcc
	v_sub_f32_e32 v108, v108, v109
	v_sub_f32_e32 v117, v107, v108
	v_add_f32_e32 v107, v74, v142
	v_add_f32_e32 v107, v107, v143
	v_add_f32_e32 v107, v107, v147
	v_add_f32_e32 v107, v107, v148
	v_mul_f32_e64 v108, |v107|, s60
	v_exp_f32_e32 v108, v108
	v_min_f32_e32 v107, 0, v107
	v_add_f32_e32 v108, 1.0, v108
	v_cmp_gt_f32_e32 vcc, s61, v108
	s_nop 1
	v_cndmask_b32_e64 v109, 0, 32, vcc
	v_ldexp_f32 v108, v108, v109
	v_log_f32_e32 v108, v108
	s_nop 0
	v_mul_f32_e32 v109, 0x3f317217, v108
	v_fma_f32 v109, v108, s62, -v109
	v_fmac_f32_e32 v109, 0x3377d1cf, v108
	v_fmac_f32_e32 v109, 0x3f317217, v108
	v_cmp_lt_f32_e64 s[6:7], |v108|, s63
	s_nop 1
	v_cndmask_b32_e64 v108, v108, v109, s[6:7]
	v_cndmask_b32_e32 v109, 0, v100, vcc
	v_sub_f32_e32 v108, v108, v109
	v_sub_f32_e32 v118, v107, v108
	v_add_f32_e32 v107, v74, v155
	v_add_f32_e32 v107, v107, v156
	v_add_f32_e32 v107, v107, v161
	v_add_f32_e32 v107, v107, v164
	v_mul_f32_e64 v108, |v107|, s60
	v_exp_f32_e32 v108, v108
	v_min_f32_e32 v107, 0, v107
	v_add_f32_e32 v108, 1.0, v108
	v_cmp_gt_f32_e32 vcc, s61, v108
	s_nop 1
	v_cndmask_b32_e64 v109, 0, 32, vcc
	v_ldexp_f32 v108, v108, v109
	v_log_f32_e32 v108, v108
	s_nop 0
	v_mul_f32_e32 v109, 0x3f317217, v108
	v_fma_f32 v109, v108, s62, -v109
	v_fmac_f32_e32 v109, 0x3377d1cf, v108
	v_fmac_f32_e32 v109, 0x3f317217, v108
	v_cmp_lt_f32_e64 s[6:7], |v108|, s63
	s_nop 1
	v_cndmask_b32_e64 v108, v108, v109, s[6:7]
	v_cndmask_b32_e32 v109, 0, v100, vcc
	v_sub_f32_e32 v108, v108, v109
	v_sub_f32_e32 v119, v107, v108
	v_add_f32_e32 v107, v74, v169
	v_add_f32_e32 v107, v107, v171
	v_add_f32_e32 v107, v107, v179
	v_add_f32_e32 v107, v107, v180
	v_mul_f32_e64 v108, |v107|, s60
	v_exp_f32_e32 v108, v108
	v_min_f32_e32 v107, 0, v107
	v_add_f32_e32 v108, 1.0, v108
	v_cmp_gt_f32_e32 vcc, s61, v108
	s_nop 1
	v_cndmask_b32_e64 v109, 0, 32, vcc
	v_ldexp_f32 v108, v108, v109
	v_log_f32_e32 v108, v108
	s_nop 0
	v_mul_f32_e32 v109, 0x3f317217, v108
	v_fma_f32 v109, v108, s62, -v109
	v_fmac_f32_e32 v109, 0x3377d1cf, v108
	v_fmac_f32_e32 v109, 0x3f317217, v108
	v_cmp_lt_f32_e64 s[6:7], |v108|, s63
	s_nop 1
	v_cndmask_b32_e64 v108, v108, v109, s[6:7]
	v_cndmask_b32_e32 v109, 0, v100, vcc
	v_sub_f32_e32 v108, v108, v109
	v_sub_f32_e32 v120, v107, v108
	v_add_f32_e32 v107, v74, v185
	v_add_f32_e32 v107, v107, v188
	v_add_f32_e32 v107, v107, v189
	v_add_f32_e32 v107, v107, v190
	v_mul_f32_e64 v108, |v107|, s60
	v_exp_f32_e32 v108, v108
	v_add_f32_e32 v74, v74, v191
	v_add_f32_e32 v74, v74, v196
	v_add_f32_e32 v74, v74, v197
	v_add_f32_e32 v108, 1.0, v108
	v_cmp_gt_f32_e32 vcc, s61, v108
	v_min_f32_e32 v107, 0, v107
	v_add_f32_e32 v74, v74, v198
	v_cndmask_b32_e64 v109, 0, 32, vcc
	v_ldexp_f32 v108, v108, v109
	v_log_f32_e32 v108, v108
	s_nop 0
	v_mul_f32_e32 v109, 0x3f317217, v108
	v_fma_f32 v109, v108, s62, -v109
	v_fmac_f32_e32 v109, 0x3377d1cf, v108
	v_fmac_f32_e32 v109, 0x3f317217, v108
	v_cmp_lt_f32_e64 s[6:7], |v108|, s63
	s_nop 1
	v_cndmask_b32_e64 v108, v108, v109, s[6:7]
	v_cndmask_b32_e32 v109, 0, v100, vcc
	v_sub_f32_e32 v108, v108, v109
	v_sub_f32_e32 v121, v107, v108
	v_mul_f32_e64 v107, |v74|, s60
	v_exp_f32_e32 v107, v107
	v_fmamk_f32 v109, v103, 0x3d800000, v110
	v_min_f32_e32 v74, 0, v74
	v_add_f32_e32 v107, 1.0, v107
	v_cmp_gt_f32_e32 vcc, s61, v107
	s_nop 1
	v_cndmask_b32_e64 v108, 0, 32, vcc
	v_ldexp_f32 v107, v107, v108
	v_log_f32_e32 v107, v107
	s_nop 0
	v_mul_f32_e32 v108, 0x3f317217, v107
	v_fma_f32 v108, v107, s62, -v108
	v_fmac_f32_e32 v108, 0x3377d1cf, v107
	v_fmac_f32_e32 v108, 0x3f317217, v107
	v_cmp_lt_f32_e64 s[6:7], |v107|, s63
	s_nop 1
	v_cndmask_b32_e64 v107, v107, v108, s[6:7]
	v_cndmask_b32_e32 v108, 0, v100, vcc
	v_sub_f32_e32 v107, v107, v108
	v_fmamk_f32 v108, v104, 0x3d800000, v109
	v_sub_f32_e32 v74, v74, v107
	v_fmamk_f32 v107, v105, 0x3d800000, v108
	v_fmamk_f32 v106, v106, 0x3d800000, v107
	v_fmamk_f32 v105, v117, 0x3d800000, v106
	v_fmamk_f32 v104, v118, 0x3d800000, v105
	v_fmamk_f32 v103, v119, 0x3d800000, v104
	v_fmamk_f32 v102, v120, 0x3d800000, v103
	v_fmamk_f32 v101, v121, 0x3d800000, v102
	v_fmamk_f32 v73, v74, 0x3d800000, v101
	v_lshl_add_u32 v74, s3, 2, v78
	ds_write_b32 v74, v73
	s_waitcnt lgkmcnt(0)
	s_barrier
	ds_read2st64_b32 v[76:77], v78 offset1:2
	ds_read2st64_b32 v[74:75], v78 offset0:4 offset1:6
	s_cselect_b64 s[6:7], -1, 0
	s_cmpk_gt_u32 s67, 0x7f
	s_waitcnt lgkmcnt(1)
	v_add_f32_e32 v76, 0, v76
	s_cbranch_scc1 .LBB0_734
	v_add_f32_e32 v117, v76, v77
	s_waitcnt lgkmcnt(0)
	v_add_f32_e32 v117, v117, v74
	v_add_f32_e32 v117, v117, v75
	v_mul_f32_e32 v117, 0x3fb8aa3b, v117
	v_exp_f32_e32 v117, v117
	ds_write_b32 v82, v117
